# feature-major in-proj units fully remapped: both units of a workgroup share one token tile, workgroups with 7 units never get the rotary tile
# speedup vs baseline: 1.0190x; 1.0084x over previous
; __device__ __forceinline__ float rowscale(const float* SS, int row) {
;     const f32x4* p = (const f32x4*)(SS + (size_t)row * 16);
;     const f32x4 a = p[0], b = p[1], c = p[2], d = p[3];
;     const float s = ((a[0] + a[1]) + (a[2] + a[3])) + ((b[0] + b[1]) + (b[2] + b[3])) + ((c[0] + c[1]) + (c[2] + c[3])) + ((d[0] + d[1]) + (d[2] + d[3]));
;     return 1.0f / sqrtf(s * (1.0f / 1024.0f) + 1e-6f);
; }
; DI void fill_rowscales(const pg8::StaticOrder& S, const float* SS, LAS float* rs, int bycol) {
;     ...
;     for (int ui = 0; ui < RS_SLOTS && S.next(ui, u); ++ui) {
;         const int t = threadIdx.x;
;         if (t < 256) rs[ui * 256 + t] = pg8::rowscale(SS, (bycol ? u.pn : u.pm) * 256 + t);
.LBB0_589:
	s_ashr_i32 s4, s16, 3
	s_add_i32 s4, s17, s4
	s_ashr_i32 s5, s4, 31
	s_lshr_b32 s5, s5, 22
	s_add_i32 s5, s4, s5
	s_ashr_i32 s16, s5, 10
	s_lshl_b32 s16, s16, 3
	s_sub_i32 s16, 4, s16
	s_min_i32 s16, s16, 8
	s_abs_i32 s17, s16
	v_cvt_f32_u32_e32 v4, s17
	s_and_b32 s5, s5, 0xfffffc00
	s_sub_i32 s4, s4, s5
	s_abs_i32 s5, s4
	v_rcp_iflag_f32_e32 v4, v4
	s_xor_b32 s4, s4, s16
	s_sub_i32 s16, 0, s17
	s_ashr_i32 s4, s4, 31
	v_mul_f32_e32 v4, 0x4f7ffffe, v4
	v_cvt_u32_f32_e32 v4, v4
	s_nop 0
	v_readfirstlane_b32 s18, v4
	s_mul_i32 s16, s16, s18
	s_mul_hi_u32 s16, s18, s16
	s_add_i32 s18, s18, s16
	s_mul_hi_u32 s16, s5, s18
	s_mul_i32 s18, s16, s17
	s_sub_i32 s5, s5, s18
	s_add_i32 s19, s16, 1
	s_sub_i32 s18, s5, s17
	s_cmp_ge_u32 s5, s17
	s_cselect_b32 s16, s19, s16
	s_cselect_b32 s5, s18, s5
	s_add_i32 s18, s16, 1
	s_cmp_ge_u32 s5, s17
	s_cselect_b32 s5, s18, s16
	s_xor_b32 s5, s5, s4
	s_sub_i32 s4, s5, s4
	s_lshr_b32 s5, s2, 3
	s_and_b32 s18, s2, 7
	s_lshl_b32 s18, s18, 4
	s_and_b32 s5, s5, 15
	s_add_i32 s5, s18, s5
	s_cmp_eq_u32 s94, 0x100
	s_cselect_b32 s4, s5, s4
	v_lshl_or_b32 v4, s4, 8, v254
	v_ashrrev_i32_e32 v5, 31, v4
	v_lshlrev_b64 v[4:5], 6, v[4:5]
	v_lshl_add_u64 v[20:21], s[12:13], 0, v[4:5]
	global_load_dwordx4 v[4:7], v[20:21], off
	global_load_dwordx4 v[8:11], v[20:21], off offset:16
	global_load_dwordx4 v[12:15], v[20:21], off offset:32
	global_load_dwordx4 v[16:19], v[20:21], off offset:48
	s_waitcnt vmcnt(3)
	v_mov_b32_e32 v20, v5
	v_mov_b32_e32 v21, v6
	v_mov_b32_e32 v5, v7
	s_waitcnt vmcnt(2)
	v_mov_b32_e32 v6, v9
	v_mov_b32_e32 v7, v10
	v_mov_b32_e32 v9, v11
	v_pk_add_f32 v[4:5], v[20:21], v[4:5]
	v_pk_add_f32 v[6:7], v[6:7], v[8:9]
	v_pk_add_f32 v[4:5], v[4:5], v[4:5] op_sel:[0,1] op_sel_hi:[1,0]
	v_pk_add_f32 v[6:7], v[6:7], v[6:7] op_sel:[0,1] op_sel_hi:[1,0]
	s_waitcnt vmcnt(1)
	v_add_f32_e32 v10, v12, v13
	v_add_f32_e32 v12, v14, v15
	s_waitcnt vmcnt(0)
	v_mov_b32_e32 v11, v18
	v_mov_b32_e32 v13, v19
	v_mov_b32_e32 v5, v16
	v_mov_b32_e32 v7, v17
	v_pk_add_f32 v[8:9], v[10:11], v[12:13]
	v_pk_add_f32 v[4:5], v[4:5], v[6:7]
	s_nop 0
	v_pk_add_f32 v[4:5], v[4:5], v[8:9]
	s_nop 0
	v_add_f32_e32 v4, v4, v5
	v_fmamk_f32 v4, v4, 0x3a800000, v2
	v_mul_f32_e32 v5, 0x4f800000, v4
	v_cmp_gt_f32_e32 vcc, s15, v4
	s_nop 1
	v_cndmask_b32_e32 v4, v4, v5, vcc
	v_sqrt_f32_e32 v5, v4
	s_nop 0
	v_add_u32_e32 v6, -1, v5
	v_add_u32_e32 v7, 1, v5
	v_fma_f32 v8, -v6, v5, v4
	v_fma_f32 v9, -v7, v5, v4
	v_cmp_ge_f32_e64 s[4:5], 0, v8
	s_nop 1
	v_cndmask_b32_e64 v5, v5, v6, s[4:5]
	v_cmp_lt_f32_e64 s[4:5], 0, v9
	s_nop 1
	v_cndmask_b32_e64 v5, v5, v7, s[4:5]
	v_mul_f32_e32 v6, 0x37800000, v5
	v_cndmask_b32_e32 v5, v5, v6, vcc
	v_cmp_class_f32_e32 vcc, v4, v3
	s_nop 1
	v_cndmask_b32_e32 v4, v5, v4, vcc
	v_div_scale_f32 v5, s[4:5], v4, v4, 1.0
	v_rcp_f32_e32 v6, v5
	v_div_scale_f32 v7, vcc, 1.0, v4, 1.0
	v_fma_f32 v8, -v5, v6, 1.0
	v_fmac_f32_e32 v6, v8, v6
	v_mul_f32_e32 v8, v7, v6
	v_fma_f32 v9, -v5, v8, v7
	v_fmac_f32_e32 v8, v9, v6
	v_fma_f32 v5, -v5, v8, v7
	v_div_fmas_f32 v5, v5, v6, v8
	v_div_fixup_f32 v4, v5, v4, 1.0
	v_add_u32_e32 v5, s14, v153
	ds_write_b32 v5, v4 offset:12288
	s_branch .LBB0_581

; #define PG8_STAGE(bufoff, gbase, voff) do { _Pragma("unroll") for (int _i = 0; _i < 2; ++_i) \
;         __builtin_amdgcn_global_load_lds((const unsigned*)((const char*)(gbase) + (voff)[_i]), (PG8_LAS unsigned*)(lds + (bufoff) + ldsw + _i * 8192), 16, 0, 0); } while (0)
; #define PG8_BAR __builtin_amdgcn_s_barrier()
; template <class Epi, class Sched, bool ALIGN_EPI = false, bool SP2 = false>
; __device__ __forceinline__ void gemm_phase(PG8_LAS unsigned char* lds, const Gemm g, const Sched& S, const Epi& E) {
;     ...
;     if (!S.next(0, cur)) return;
;     f32x4 acc[2][2][4][2];
; #pragma unroll
;     for (int a = 0; a < 2; ++a)
; #pragma unroll
;         for (int b = 0; b < 2; ++b)
; #pragma unroll
;             for (int m = 0; m < 4; ++m)
; #pragma unroll
;                 for (int n = 0; n < 2; ++n) acc[a][b][m][n] = (f32x4){0.f, 0.f, 0.f, 0.f};
;     bf16x8 At[4][2], B0[2][2], B1[2][2];
;     const char* cA = (const char*)g.A + (size_t)cur.pm * tstep; const char* cB = (const char*)g.Bt + (size_t)cur.pn * tstep;
;     S.a_ready(cur, 0);
;     if constexpr (SP2) {
;         PG8_STAGE(PG8_SB(0, 0), cB, voffB); PG8_STAGE(PG8_SB(0, 1), cB + hstep, voffB); PG8_STAGE(PG8_SA(0, 0), cA, voffA); PG8_STAGE(PG8_SA(0, 1), cA + hstep, voffA);
;         if (wr == 1) PG8_BAR;
.LBB0_595:
	s_lshr_b32 s1, s4, 6
	s_ashr_i32 s0, s5, 3
	s_lshr_b32 s5, s4, 8
	s_lshl_b32 s33, s1, 10
	s_add_u32 s36, s90, 0x1600000
	s_addc_u32 s37, s91, 0
	s_add_i32 s0, s6, s0
	s_ashr_i32 s6, s0, 31
	s_lshr_b32 s6, s6, 22
	s_add_i32 s6, s0, s6
	s_ashr_i32 s6, s6, 10
	s_lshl_b32 s8, s6, 3
	s_sub_i32 s7, 4, s8
	s_lshl_b32 s6, s6, 10
	s_min_u32 s9, s7, 8
	s_sub_i32 s12, s0, s6
	s_sext_i32_i16 s0, s12
	v_cvt_f32_ubyte0_e32 v1, s9
	v_cvt_f32_i32_e32 v0, s0
	v_rcp_iflag_f32_e32 v2, v1
	s_ashr_i32 s0, s0, 30
	s_or_b32 s0, s0, 1
	v_mov_b32_e32 v139, 0
	v_mul_f32_e32 v2, v0, v2
	v_trunc_f32_e32 v2, v2
	v_fma_f32 v0, -v2, v1, v0
	v_cvt_i32_f32_e32 v2, v2
	v_cmp_ge_f32_e64 s[6:7], |v0|, v1
	s_and_b64 s[6:7], s[6:7], exec
	s_cselect_b32 s0, s0, 0
	v_readfirstlane_b32 s6, v2
	s_add_i32 s0, s6, s0
	s_mul_i32 s6, s0, s9
	s_sub_i32 s6, s12, s6
	s_sext_i32_i16 s6, s6
	s_add_i32 s26, s8, s6
	s_lshr_b32 s6, s2, 3
	s_and_b32 s7, s2, 7
	s_lshl_b32 s7, s7, 4
	s_and_b32 s8, s6, 15
	s_add_i32 s7, s7, s8
	s_lshr_b32 s6, s6, 4
	s_lshl_b32 s6, s6, 1
	s_cmp_eq_u32 s94, 0x100
	s_cselect_b32 s0, s7, s0
	s_cselect_b32 s26, s6, s26
	s_ashr_i32 s27, s26, 31
	s_bfe_i64 s[8:9], s[0:1], 0x100000
	s_lshl_b64 s[6:7], s[26:27], 19
	s_lshl_b64 s[8:9], s[8:9], 19
	s_add_u32 s30, s48, s8
	s_addc_u32 s31, s49, s9
	s_add_i32 s38, s33, 0
	s_add_i32 m0, s38, 0x10000
	v_mov_b32_e32 v143, v139
	global_load_lds_dwordx4 v138, s[30:31]
	s_add_i32 m0, s38, 0x12000
	s_add_u32 s8, s30, 0x40000
	global_load_lds_dwordx4 v142, s[30:31]
	s_addc_u32 s9, s31, 0
	s_add_i32 m0, s38, 0x14000
	v_mov_b32_e32 v137, v139
	global_load_lds_dwordx4 v138, s[8:9]
	s_add_i32 m0, s38, 0x16000
	s_add_u32 s28, s36, s6
	s_addc_u32 s29, s37, s7
	s_add_i32 s39, s38, 0x2000
	global_load_lds_dwordx4 v142, s[8:9]
	s_mov_b32 m0, s38
	s_add_u32 s6, s28, 0x40000
	global_load_lds_dwordx4 v136, s[28:29]
	s_mov_b32 m0, s39
	s_addc_u32 s7, s29, 0
	s_add_i32 s40, s38, 0x4000
	global_load_lds_dwordx4 v140, s[28:29]
	s_mov_b32 m0, s40
	s_add_i32 s41, s38, 0x6000
	global_load_lds_dwordx4 v136, s[6:7]
	s_mov_b32 m0, s41
	v_mov_b32_e32 v141, v139
	global_load_lds_dwordx4 v140, s[6:7]
	s_cmp_eq_u32 s5, 1
	s_mov_b32 s27, 0
	v_lshl_add_u64 v[6:7], s[30:31], 0, v[138:139]
	v_lshl_add_u64 v[4:5], s[30:31], 0, v[142:143]
	v_lshl_add_u64 v[2:3], s[28:29], 0, v[136:137]
	v_lshl_add_u64 v[0:1], s[28:29], 0, v[140:141]
	s_cselect_b64 s[6:7], -1, 0
	s_cmp_lg_u32 s5, 1
	s_mov_b32 s18, 0xbbb906ce
	s_cbranch_scc1 .LBB0_597
	s_mov_b32 s18, 0xbc3963dd
	s_barrier

;     __host__ __device__ bool next(int i, Unit& u) const {
;         const long L = (long)i * G + c; if (L >= nwg) return false;
;         int wgid = (int)L; { const int q = nwg / NXCD, r = nwg % NXCD, xcd = wgid % NXCD, off = wgid / NXCD; wgid = (xcd < r ? xcd * (q + 1) : r * (q + 1) + (xcd - r) * q) + off; }
;         const int nig = WGM * nN, gid = wgid / nig, fm = gid * WGM, gsz = (nM - fm) < WGM ? (nM - fm) : WGM;
;         u.pm = fm + ((wgid % nig) % gsz); u.pn = (wgid % nig) / gsz; return true;
; template <class Epi, class Sched, bool ALIGN_EPI = false, bool SP2 = false>
; __device__ __forceinline__ void gemm_phase(PG8_LAS unsigned char* lds, const Gemm g, const Sched& S, const Epi& E) {
;     ...
;         const bool has_next = S.next(ui + 1, nxt);
;         const char* nA = has_next ? (const char*)g.A + (size_t)nxt.pm * tstep : cA; const char* nB = has_next ? (const char*)g.Bt + (size_t)nxt.pn * tstep : cB;
.LBB0_605:
	s_ashr_i32 s18, s20, 3
	s_add_i32 s18, s22, s18
	s_ashr_i32 s19, s18, 31
	s_lshr_b32 s19, s19, 22
	s_add_i32 s19, s18, s19
	s_ashr_i32 s20, s19, 10
	s_lshl_b32 s20, s20, 3
	s_sub_i32 s21, 4, s20
	s_min_i32 s21, s21, 8
	s_abs_i32 s22, s21
	v_cvt_f32_u32_e32 v0, s22
	s_sub_i32 s24, 0, s22
	s_and_b32 s19, s19, 0xfffffc00
	s_sub_i32 s19, s18, s19
	v_rcp_iflag_f32_e32 v0, v0
	s_abs_i32 s18, s19
	s_xor_b32 s23, s19, s21
	s_ashr_i32 s23, s23, 31
	v_mul_f32_e32 v0, 0x4f7ffffe, v0
	v_cvt_u32_f32_e32 v0, v0
	s_nop 0
	v_readfirstlane_b32 s25, v0
	s_mul_i32 s24, s24, s25
	s_mul_hi_u32 s24, s25, s24
	s_add_i32 s25, s25, s24
	s_mul_hi_u32 s24, s18, s25
	s_mul_i32 s25, s24, s22
	s_sub_i32 s18, s18, s25
	s_add_i32 s34, s24, 1
	s_sub_i32 s25, s18, s22
	s_cmp_ge_u32 s18, s22
	s_cselect_b32 s24, s34, s24
	s_cselect_b32 s18, s25, s18
	s_add_i32 s25, s24, 1
	s_cmp_ge_u32 s18, s22
	s_cselect_b32 s18, s25, s24
	s_xor_b32 s18, s18, s23
	s_sub_i32 s18, s18, s23
	s_mul_i32 s21, s18, s21
	s_sub_i32 s19, s19, s21
	s_add_i32 s20, s20, s19
	s_lshr_b32 s19, s2, 3
	s_and_b32 s21, s2, 7
	s_lshl_b32 s21, s21, 4
	s_and_b32 s22, s19, 15
	s_add_i32 s21, s21, s22
	s_lshr_b32 s19, s19, 4
	s_lshl_b32 s19, s19, 1
	s_add_i32 s19, s19, s53
	s_cmp_eq_u32 s94, 0x100
	s_cselect_b32 s18, s21, s18
	s_cselect_b32 s20, s19, s20

; #define PG8_STAGE(bufoff, gbase, voff) do { _Pragma("unroll") for (int _i = 0; _i < 2; ++_i) \
;         __builtin_amdgcn_global_load_lds((const unsigned*)((const char*)(gbase) + (voff)[_i]), (PG8_LAS unsigned*)(lds + (bufoff) + ldsw + _i * 8192), 16, 0, 0); } while (0)
; #define PG8_BAR __builtin_amdgcn_s_barrier()
; template <class Epi, class Sched, bool ALIGN_EPI = false, bool SP2 = false>
; __device__ __forceinline__ void gemm_phase(PG8_LAS unsigned char* lds, const Gemm g, const Sched& S, const Epi& E) {
;     ...
;     if (!S.next(0, cur)) return;
;     f32x4 acc[2][2][4][2];
; #pragma unroll
;     for (int a = 0; a < 2; ++a)
; #pragma unroll
;         for (int b = 0; b < 2; ++b)
; #pragma unroll
;             for (int m = 0; m < 4; ++m)
; #pragma unroll
;                 for (int n = 0; n < 2; ++n) acc[a][b][m][n] = (f32x4){0.f, 0.f, 0.f, 0.f};
;     bf16x8 At[4][2], B0[2][2], B1[2][2];
;     const char* cA = (const char*)g.A + (size_t)cur.pm * tstep; const char* cB = (const char*)g.Bt + (size_t)cur.pn * tstep;
;     S.a_ready(cur, 0);
;     if constexpr (SP2) {
;         PG8_STAGE(PG8_SB(0, 0), cB, voffB); PG8_STAGE(PG8_SB(0, 1), cB + hstep, voffB); PG8_STAGE(PG8_SA(0, 0), cA, voffA); PG8_STAGE(PG8_SA(0, 1), cA + hstep, voffA);
;         if (wr == 1) PG8_BAR;
.LBB0_1477:
	s_lshr_b32 s1, s4, 6
	s_ashr_i32 s0, s5, 3
	s_lshr_b32 s5, s4, 8
	s_lshl_b32 s33, s1, 10
	s_add_u32 s36, s90, 0x4000000
	s_addc_u32 s37, s91, 0
	s_add_i32 s0, s6, s0
	s_ashr_i32 s6, s0, 31
	s_lshr_b32 s6, s6, 22
	s_add_i32 s6, s0, s6
	s_ashr_i32 s6, s6, 10
	s_lshl_b32 s8, s6, 3
	s_sub_i32 s7, 4, s8
	s_lshl_b32 s6, s6, 10
	s_min_u32 s9, s7, 8
	s_sub_i32 s12, s0, s6
	s_sext_i32_i16 s0, s12
	v_cvt_f32_ubyte0_e32 v1, s9
	v_cvt_f32_i32_e32 v0, s0
	v_rcp_iflag_f32_e32 v2, v1
	s_ashr_i32 s0, s0, 30
	s_or_b32 s0, s0, 1
	v_mov_b32_e32 v139, 0
	v_mul_f32_e32 v2, v0, v2
	v_trunc_f32_e32 v2, v2
	v_fma_f32 v0, -v2, v1, v0
	v_cvt_i32_f32_e32 v2, v2
	v_cmp_ge_f32_e64 s[6:7], |v0|, v1
	s_and_b64 s[6:7], s[6:7], exec
	s_cselect_b32 s0, s0, 0
	v_readfirstlane_b32 s6, v2
	s_add_i32 s0, s6, s0
	s_mul_i32 s6, s0, s9
	s_sub_i32 s6, s12, s6
	s_sext_i32_i16 s6, s6
	s_add_i32 s26, s8, s6
	s_lshr_b32 s6, s2, 3
	s_and_b32 s7, s2, 7
	s_lshl_b32 s7, s7, 4
	s_and_b32 s8, s6, 15
	s_add_i32 s7, s7, s8
	s_lshr_b32 s6, s6, 4
	s_lshl_b32 s6, s6, 1
	s_cmp_eq_u32 s94, 0x100
	s_cselect_b32 s0, s7, s0
	s_cselect_b32 s26, s6, s26
	s_ashr_i32 s27, s26, 31
	s_bfe_i64 s[8:9], s[0:1], 0x100000
	s_lshl_b64 s[6:7], s[26:27], 19
	s_lshl_b64 s[8:9], s[8:9], 19
	s_add_u32 s30, s48, s8
	s_addc_u32 s31, s49, s9
	s_add_i32 s38, s33, 0
	s_add_i32 m0, s38, 0x10000
	v_mov_b32_e32 v143, v139
	global_load_lds_dwordx4 v138, s[30:31]
	s_add_i32 m0, s38, 0x12000
	s_add_u32 s8, s30, 0x40000
	global_load_lds_dwordx4 v142, s[30:31]
	s_addc_u32 s9, s31, 0
	s_add_i32 m0, s38, 0x14000
	v_mov_b32_e32 v137, v139
	global_load_lds_dwordx4 v138, s[8:9]
	s_add_i32 m0, s38, 0x16000
	s_add_u32 s28, s36, s6
	s_addc_u32 s29, s37, s7
	s_add_i32 s39, s38, 0x2000
	global_load_lds_dwordx4 v142, s[8:9]
	s_mov_b32 m0, s38
	s_add_u32 s6, s28, 0x40000
	global_load_lds_dwordx4 v136, s[28:29]
	s_mov_b32 m0, s39
	s_addc_u32 s7, s29, 0
	s_add_i32 s40, s38, 0x4000
	global_load_lds_dwordx4 v140, s[28:29]
	s_mov_b32 m0, s40
	s_add_i32 s41, s38, 0x6000
	global_load_lds_dwordx4 v136, s[6:7]
	s_mov_b32 m0, s41
	v_mov_b32_e32 v141, v139
	global_load_lds_dwordx4 v140, s[6:7]
	s_cmp_eq_u32 s5, 1
	s_mov_b32 s27, 0
	v_lshl_add_u64 v[6:7], s[30:31], 0, v[138:139]
	v_lshl_add_u64 v[4:5], s[30:31], 0, v[142:143]
	v_lshl_add_u64 v[2:3], s[28:29], 0, v[136:137]
	v_lshl_add_u64 v[0:1], s[28:29], 0, v[140:141]
	s_cselect_b64 s[6:7], -1, 0
	s_cmp_lg_u32 s5, 1
	s_mov_b32 s18, 0xbbb906ce
	s_cbranch_scc1 .LBB0_1479
	s_mov_b32 s18, 0xbc3963dd
	s_barrier
